# ada GEMM: drop MFMAs and LDS frag reads for all-zero padding rows (m>=1 of ai=1 half) on top of early-inv barrier
# speedup vs baseline: 1.0536x; 1.0058x over previous
.LBB0_103:
	ds_read_b128 v[136:139], v150
	ds_read_b128 v[154:157], v150 offset:1024
	ds_read_b128 v[158:161], v150 offset:2048
	ds_read_b128 v[162:165], v150 offset:3072
	ds_read_b128 v[166:169], v151
	ds_read_b128 v[170:173], v151 offset:1024
	ds_read_b128 v[176:179], v151 offset:2048
	ds_read_b128 v[180:183], v151 offset:3072
	s_add_u32 s4, vcc_lo, 0xfffc0080
	s_addc_u32 s5, vcc_hi, -1
	s_cmp_eq_u32 s36, 12
	s_cselect_b32 s5, s24, s5
	s_cselect_b32 s4, s25, s4
	s_cselect_b32 s9, s26, s31
	s_cselect_b32 s8, s27, s30
	v_lshl_add_u64 v[140:141], vcc, 0, v[132:133]
	s_add_i32 m0, s11, 0xc000
	ds_read_b128 v[184:187], v152
	ds_read_b128 v[188:191], v152 offset:1024
	ds_read_b128 v[192:195], v152 offset:2048
	ds_read_b128 v[196:199], v152 offset:3072
	ds_read_b128 v[200:203], v152 offset:4096
	ds_read_b128 v[204:207], v152 offset:5120
	ds_read_b128 v[208:211], v152 offset:6144
	ds_read_b128 v[212:215], v152 offset:7168
	global_load_lds_dwordx4 v[140:141], off
	v_lshl_add_u64 v[140:141], vcc, 0, v[134:135]
	s_add_i32 m0, s11, 0xe000
	s_nop 0
	global_load_lds_dwordx4 v[140:141], off
	s_waitcnt vmcnt(8)
	s_waitcnt lgkmcnt(0)
	s_barrier
	s_setprio 1
	s_waitcnt lgkmcnt(0)
	v_mfma_f32_16x16x32_bf16 v[124:127], v[136:139], v[184:187], v[124:127]
	v_mfma_f32_16x16x32_bf16 v[120:123], v[158:161], v[184:187], v[120:123]
	v_mfma_f32_16x16x32_bf16 v[112:115], v[136:139], v[192:195], v[112:115]
	v_mfma_f32_16x16x32_bf16 v[104:107], v[158:161], v[192:195], v[104:107]
	v_mfma_f32_16x16x32_bf16 v[96:99], v[136:139], v[200:203], v[96:99]
	v_mfma_f32_16x16x32_bf16 v[88:91], v[158:161], v[200:203], v[88:91]
	v_mfma_f32_16x16x32_bf16 v[80:83], v[136:139], v[208:211], v[80:83]
	v_mfma_f32_16x16x32_bf16 v[72:75], v[158:161], v[208:211], v[72:75]
	v_mfma_f32_16x16x32_bf16 v[124:127], v[154:157], v[188:191], v[124:127]
	v_mfma_f32_16x16x32_bf16 v[120:123], v[162:165], v[188:191], v[120:123]
	v_mfma_f32_16x16x32_bf16 v[112:115], v[154:157], v[196:199], v[112:115]
	v_mfma_f32_16x16x32_bf16 v[104:107], v[162:165], v[196:199], v[104:107]
	v_mfma_f32_16x16x32_bf16 v[96:99], v[154:157], v[204:207], v[96:99]
	v_mfma_f32_16x16x32_bf16 v[88:91], v[162:165], v[204:207], v[88:91]
	v_mfma_f32_16x16x32_bf16 v[80:83], v[154:157], v[212:215], v[80:83]
	v_mfma_f32_16x16x32_bf16 v[72:75], v[162:165], v[212:215], v[72:75]
	s_setprio 0
	s_setprio 1
	v_mfma_f32_16x16x32_bf16 v[116:119], v[166:169], v[184:187], v[116:119]
	v_mfma_f32_16x16x32_bf16 v[108:111], v[176:179], v[184:187], v[108:111]
	v_mfma_f32_16x16x32_bf16 v[100:103], v[166:169], v[192:195], v[100:103]
	v_mfma_f32_16x16x32_bf16 v[92:95], v[176:179], v[192:195], v[92:95]
	v_mfma_f32_16x16x32_bf16 v[84:87], v[166:169], v[200:203], v[84:87]
	v_mfma_f32_16x16x32_bf16 v[76:79], v[176:179], v[200:203], v[76:79]
	v_mfma_f32_16x16x32_bf16 v[68:71], v[166:169], v[208:211], v[68:71]
	v_mfma_f32_16x16x32_bf16 v[64:67], v[176:179], v[208:211], v[64:67]
	v_mfma_f32_16x16x32_bf16 v[116:119], v[170:173], v[188:191], v[116:119]
	v_mfma_f32_16x16x32_bf16 v[108:111], v[180:183], v[188:191], v[108:111]
	v_mfma_f32_16x16x32_bf16 v[100:103], v[170:173], v[196:199], v[100:103]
	v_mfma_f32_16x16x32_bf16 v[92:95], v[180:183], v[196:199], v[92:95]
	v_mfma_f32_16x16x32_bf16 v[84:87], v[170:173], v[204:207], v[84:87]
	v_mfma_f32_16x16x32_bf16 v[76:79], v[180:183], v[204:207], v[76:79]
	v_mfma_f32_16x16x32_bf16 v[68:71], v[170:173], v[212:215], v[68:71]
	v_mfma_f32_16x16x32_bf16 v[64:67], v[180:183], v[212:215], v[64:67]
	s_setprio 0
	s_barrier
	s_add_i32 s37, s20, s10
	v_lshl_add_u64 v[140:141], s[8:9], 0, v[128:129]
	s_mov_b32 m0, s37
	ds_read_b128 v[184:187], v152 offset:16384
	ds_read_b128 v[188:191], v152 offset:17408
	global_load_lds_dwordx4 v[140:141], off
	s_add_i32 m0, s37, 0x2000
	s_add_u32 s38, s8, 0x40000
	v_lshl_add_u64 v[216:217], s[8:9], 0, v[130:131]
	s_addc_u32 s39, s9, 0
	s_add_i32 s37, s21, s10
	global_load_lds_dwordx4 v[216:217], off
	v_lshl_add_u64 v[218:219], s[38:39], 0, v[128:129]
	s_mov_b32 m0, s37
	v_lshl_add_u64 v[220:221], s[4:5], 0, v[130:131]
	global_load_lds_dwordx4 v[218:219], off
	v_lshl_add_u64 v[218:219], s[38:39], 0, v[130:131]
	s_add_i32 m0, s37, 0x2000
	s_nop 0
	global_load_lds_dwordx4 v[218:219], off
	v_lshl_add_u64 v[218:219], s[4:5], 0, v[128:129]
	s_mov_b32 m0, s11
	s_nop 0
	global_load_lds_dwordx4 v[218:219], off
	s_mov_b32 m0, s12
	s_nop 0
	global_load_lds_dwordx4 v[220:221], off
	s_waitcnt vmcnt(8)
	s_waitcnt lgkmcnt(0)
	s_barrier
	s_setprio 1
	s_waitcnt lgkmcnt(0)
	v_mfma_f32_16x16x32_bf16 v[60:63], v[136:139], v[184:187], v[60:63]
	v_mfma_f32_16x16x32_bf16 v[56:59], v[158:161], v[184:187], v[56:59]
	v_mfma_f32_16x16x32_bf16 v[60:63], v[154:157], v[188:191], v[60:63]
	v_mfma_f32_16x16x32_bf16 v[56:59], v[162:165], v[188:191], v[56:59]
	s_setprio 0
	s_setprio 1
	v_mfma_f32_16x16x32_bf16 v[52:55], v[166:169], v[184:187], v[52:55]
	v_mfma_f32_16x16x32_bf16 v[44:47], v[176:179], v[184:187], v[44:47]
	v_mfma_f32_16x16x32_bf16 v[52:55], v[170:173], v[188:191], v[52:55]
	v_mfma_f32_16x16x32_bf16 v[44:47], v[180:183], v[188:191], v[44:47]
	s_setprio 0
	s_barrier
	s_add_i32 s37, 0, 0x18000
	v_add_u32_e32 v153, s37, v144
	s_add_i32 s38, 0, 0x1c000
	ds_read_b128 v[136:139], v153
	ds_read_b128 v[154:157], v153 offset:1024
	ds_read_b128 v[158:161], v153 offset:2048
	ds_read_b128 v[162:165], v153 offset:3072
	v_add_u32_e32 v153, s38, v144
	ds_read_b128 v[166:169], v153
	ds_read_b128 v[170:173], v153 offset:1024
	ds_read_b128 v[176:179], v153 offset:2048
	ds_read_b128 v[180:183], v153 offset:3072
	s_add_u32 s4, s4, 0x40000
	s_addc_u32 s5, s5, 0
	s_mov_b32 m0, s13
	v_lshl_add_u64 v[222:223], s[4:5], 0, v[128:129]
	ds_read_b128 v[184:187], v152 offset:32768
	ds_read_b128 v[188:191], v152 offset:33792
	ds_read_b128 v[192:195], v152 offset:34816
	ds_read_b128 v[196:199], v152 offset:35840
	ds_read_b128 v[200:203], v152 offset:36864
	ds_read_b128 v[204:207], v152 offset:37888
	ds_read_b128 v[208:211], v152 offset:38912
	ds_read_b128 v[212:215], v152 offset:39936
	global_load_lds_dwordx4 v[222:223], off
	v_lshl_add_u64 v[222:223], s[4:5], 0, v[130:131]
	s_mov_b32 m0, s14
	s_nop 0
	global_load_lds_dwordx4 v[222:223], off
	s_waitcnt vmcnt(8)
	s_waitcnt lgkmcnt(0)
	s_barrier
	s_setprio 1
	s_waitcnt lgkmcnt(0)
	v_mfma_f32_16x16x32_bf16 v[124:127], v[136:139], v[184:187], v[124:127]
	v_mfma_f32_16x16x32_bf16 v[120:123], v[158:161], v[184:187], v[120:123]
	v_mfma_f32_16x16x32_bf16 v[112:115], v[136:139], v[192:195], v[112:115]
	v_mfma_f32_16x16x32_bf16 v[104:107], v[158:161], v[192:195], v[104:107]
	v_mfma_f32_16x16x32_bf16 v[96:99], v[136:139], v[200:203], v[96:99]
	v_mfma_f32_16x16x32_bf16 v[88:91], v[158:161], v[200:203], v[88:91]
	v_mfma_f32_16x16x32_bf16 v[80:83], v[136:139], v[208:211], v[80:83]
	v_mfma_f32_16x16x32_bf16 v[72:75], v[158:161], v[208:211], v[72:75]
	v_mfma_f32_16x16x32_bf16 v[124:127], v[154:157], v[188:191], v[124:127]
	v_mfma_f32_16x16x32_bf16 v[120:123], v[162:165], v[188:191], v[120:123]
	v_mfma_f32_16x16x32_bf16 v[112:115], v[154:157], v[196:199], v[112:115]
	v_mfma_f32_16x16x32_bf16 v[104:107], v[162:165], v[196:199], v[104:107]
	v_mfma_f32_16x16x32_bf16 v[96:99], v[154:157], v[204:207], v[96:99]
	v_mfma_f32_16x16x32_bf16 v[88:91], v[162:165], v[204:207], v[88:91]
	v_mfma_f32_16x16x32_bf16 v[80:83], v[154:157], v[212:215], v[80:83]
	v_mfma_f32_16x16x32_bf16 v[72:75], v[162:165], v[212:215], v[72:75]
	s_setprio 0
	s_setprio 1
	v_mfma_f32_16x16x32_bf16 v[116:119], v[166:169], v[184:187], v[116:119]
	v_mfma_f32_16x16x32_bf16 v[108:111], v[176:179], v[184:187], v[108:111]
	v_mfma_f32_16x16x32_bf16 v[100:103], v[166:169], v[192:195], v[100:103]
	v_mfma_f32_16x16x32_bf16 v[92:95], v[176:179], v[192:195], v[92:95]
	v_mfma_f32_16x16x32_bf16 v[84:87], v[166:169], v[200:203], v[84:87]
	v_mfma_f32_16x16x32_bf16 v[76:79], v[176:179], v[200:203], v[76:79]
	v_mfma_f32_16x16x32_bf16 v[68:71], v[166:169], v[208:211], v[68:71]
	v_mfma_f32_16x16x32_bf16 v[64:67], v[176:179], v[208:211], v[64:67]
	v_mfma_f32_16x16x32_bf16 v[116:119], v[170:173], v[188:191], v[116:119]
	v_mfma_f32_16x16x32_bf16 v[108:111], v[180:183], v[188:191], v[108:111]
	v_mfma_f32_16x16x32_bf16 v[100:103], v[170:173], v[196:199], v[100:103]
	v_mfma_f32_16x16x32_bf16 v[92:95], v[180:183], v[196:199], v[92:95]
	v_mfma_f32_16x16x32_bf16 v[84:87], v[170:173], v[204:207], v[84:87]
	v_mfma_f32_16x16x32_bf16 v[76:79], v[180:183], v[204:207], v[76:79]
	v_mfma_f32_16x16x32_bf16 v[68:71], v[170:173], v[212:215], v[68:71]
	v_mfma_f32_16x16x32_bf16 v[64:67], v[180:183], v[212:215], v[64:67]
	s_setprio 0
	s_barrier
	s_add_i32 s4, s37, s10
	v_lshl_add_u64 v[140:141], v[140:141], 0, s[88:89]
	s_mov_b32 m0, s4
	ds_read_b128 v[184:187], v152 offset:49152
	ds_read_b128 v[188:191], v152 offset:50176
	global_load_lds_dwordx4 v[140:141], off
	s_add_i32 m0, s4, 0x2000
	s_add_u32 s4, s8, 0x40080
	v_lshl_add_u64 v[140:141], v[216:217], 0, s[88:89]
	s_addc_u32 s5, s9, 0
	s_add_i32 s8, s38, s10
	global_load_lds_dwordx4 v[140:141], off
	v_lshl_add_u64 v[140:141], s[4:5], 0, v[128:129]
	s_mov_b32 m0, s8
	s_nop 0
	global_load_lds_dwordx4 v[140:141], off
	v_lshl_add_u64 v[140:141], s[4:5], 0, v[130:131]
	s_add_i32 m0, s8, 0x2000
	s_nop 0
	global_load_lds_dwordx4 v[140:141], off
	v_lshl_add_u64 v[140:141], v[218:219], 0, s[88:89]
	s_mov_b32 m0, s16
	s_nop 0
	global_load_lds_dwordx4 v[140:141], off
	v_lshl_add_u64 v[140:141], v[220:221], 0, s[88:89]
	s_mov_b32 m0, s17
	s_nop 0
	global_load_lds_dwordx4 v[140:141], off
	s_waitcnt vmcnt(8)
	s_waitcnt lgkmcnt(0)
	s_barrier
	s_setprio 1
	s_waitcnt lgkmcnt(0)
	v_mfma_f32_16x16x32_bf16 v[60:63], v[136:139], v[184:187], v[60:63]
	v_mfma_f32_16x16x32_bf16 v[56:59], v[158:161], v[184:187], v[56:59]
	v_mfma_f32_16x16x32_bf16 v[60:63], v[154:157], v[188:191], v[60:63]
	v_mfma_f32_16x16x32_bf16 v[56:59], v[162:165], v[188:191], v[56:59]
	s_setprio 0
	s_setprio 1
	v_mfma_f32_16x16x32_bf16 v[52:55], v[166:169], v[184:187], v[52:55]
	v_mfma_f32_16x16x32_bf16 v[44:47], v[176:179], v[184:187], v[44:47]
	v_mfma_f32_16x16x32_bf16 v[52:55], v[170:173], v[188:191], v[52:55]
	v_mfma_f32_16x16x32_bf16 v[44:47], v[180:183], v[188:191], v[44:47]
	s_setprio 0
	s_barrier
	s_add_i32 s36, s36, 2
	s_add_u32 vcc_lo, vcc_lo, 0x100
	s_addc_u32 vcc_hi, vcc_hi, 0
	s_add_u32 s30, s30, 0x100
	s_addc_u32 s31, s31, 0
	s_cmp_gt_u32 s36, 13
	s_cbranch_scc0 .LBB0_103
	s_and_b64 vcc, exec, s[90:91]
	s_cbranch_vccz .LBB0_106
	s_barrier
